# attention tile loop: cost-weighted VALU spacing (softmax stream cut into MFMA gaps by issue cost, exp = 8 / other = 4, about 24 cycles per gap) instead of by instruction count; same instruction order
# speedup vs baseline: 1.0065x; 1.0006x over previous
; __device__ __forceinline__ void diff_unit_lds(LAS unsigned char* lds, const bf16* Qd, const bf16* Kd, const bf16* VdT, bf16* MIX, const float* ghead, float lam, int head, int u, int wave, int lane) {
;     ...
;             for (int ds = 0; ds < 4; ++ds) S0 = MFMA32(*(const LAS bf16x8*)(st + koff + (((2 * ds + h) ^ kx) << 4)), qf[ds], S0);
;             if (!part) {
; #pragma unroll
;                 for (int ds = 0; ds < 4; ++ds) S1 = MFMA32(*(const LAS bf16x8*)(st + koff + 4096 + (((2 * ds + h) ^ kx) << 4)), qf[ds], S1);
;             }
;             float tmax = S0[0];
; #pragma unroll
;             for (int i = 1; i < 16; ++i) tmax = fmaxf(tmax, S0[i]);
;             if (masked) tmax = -1e30f;
;             if (!part) {
; #pragma unroll
;                 for (int i = 0; i < 16; ++i) tmax = fmaxf(tmax, S1[i]);
;             }
;             tmax = fmaxf(tmax, xhalf(tmax, h));
;             if (T == 0 || __any(tmax > 8.0f)) {
;                 const float delta = (T == 0) ? tmax : fmaxf(tmax, 0.f), alpha = (T == 0) ? 1.0f : __builtin_amdgcn_exp2f(-delta);
;                 l *= alpha;
; #pragma unroll
;                 for (int b = 0; b < 4; ++b)
; #pragma unroll
;                     for (int i = 0; i < 16; ++i) O[b][i] *= alpha;
;                 m_used += delta;
; #pragma unroll
;                 for (int i = 0; i < 16; ++i) { NEGM[i] = -m_used; S0[i] -= delta; S1[i] -= delta; }
;             }
;             {
;                 float p[16]; float ps = 0.f;
; #pragma unroll
;                 for (int i = 0; i < 16; ++i) { p[i] = __builtin_amdgcn_exp2f(S0[i]); ps += p[i]; }
;                 if (masked) {
; #pragma unroll
;                     for (int i = 0; i < 16; ++i) p[i] = 0.f;
;                     ps = 0.f;
;                 }
;                 l += ps;
;                 const bf16x8 pk0 = pack8(p[0], p[1], p[2], p[3], p[4], p[5], p[6], p[7]);
;                 const bf16x8 pk1 = pack8(p[8], p[9], p[10], p[11], p[12], p[13], p[14], p[15]);
; #pragma unroll
;                 for (int b = 0; b < 4; ++b) {
;                     const bf16x8 v0 = *(const LAS bf16x8*)(st + voff + b * 4096 + (((2 * h) ^ vx) << 4));
;                     const bf16x8 v1 = *(const LAS bf16x8*)(st + voff + b * 4096 + (((2 * h + 1) ^ vx) << 4));
;                     O[b] = MFMA32(v0, pk0, O[b]); O[b] = MFMA32(v1, pk1, O[b]);
;                 }
;             }
.Lq_rec_e:
	v_mfma_f32_32x32x16_bf16 v[2:17], v[234:237], v[82:85], v[2:17]
	ds_read_b128 v[234:237], v208 offset:28672
	v_exp_f32_e32 v98, v98
	v_exp_f32_e32 v99, v99
	v_exp_f32_e32 v100, v100
	v_mfma_f32_32x32x16_bf16 v[50:65], v[238:241], v[86:89], v[50:65]
	ds_read_b128 v[238:241], v213 offset:16384
	v_add_f32_e32 v251, v98, v99
	v_exp_f32_e32 v101, v101
	v_exp_f32_e32 v102, v102
	v_add_f32_e32 v251, v251, v100
	v_mfma_f32_32x32x16_bf16 v[34:49], v[242:245], v[86:89], v[34:49]
	ds_read_b128 v[242:245], v213 offset:20480
	v_exp_f32_e32 v103, v103
	v_add_f32_e32 v251, v251, v101
	v_exp_f32_e32 v104, v104
	v_add_f32_e32 v251, v251, v102
	v_mfma_f32_32x32x16_bf16 v[18:33], v[246:249], v[86:89], v[18:33]
	ds_read_b128 v[246:249], v213 offset:24576
	v_exp_f32_e32 v105, v105
	v_add_f32_e32 v251, v251, v103
	v_cvt_pk_bf16_f32 v98, v98, v99
	v_add_f32_e32 v251, v251, v104
	v_cvt_pk_bf16_f32 v99, v100, v101
	v_mfma_f32_32x32x16_bf16 v[2:17], v[252:255], v[86:89], v[2:17]
	ds_read_b128 v[252:255], v213 offset:28672
	v_cvt_pk_bf16_f32 v100, v102, v103
	v_cvt_pk_bf16_f32 v101, v104, v105
	v_add_f32_e32 v251, v251, v105
	v_exp_f32_e32 v106, v106
	v_exp_f32_e32 v107, v107
	s_cmp_lg_u32 s59, 0
	s_cbranch_scc1 .Lq_rl_e
.Lq_rlc_e:
	s_waitcnt lgkmcnt(8)
	v_mfma_f32_32x32x16_bf16 v[82:97], v[164:167], v[126:129], v[66:81]
	v_exp_f32_e32 v108, v108
	v_add_f32_e32 v251, v251, v106
	v_exp_f32_e32 v109, v109
	v_add_f32_e32 v251, v251, v107
	v_mfma_f32_32x32x16_bf16 v[82:97], v[168:171], v[122:125], v[82:97]
	v_exp_f32_e32 v110, v110
	v_add_f32_e32 v251, v251, v108
	v_exp_f32_e32 v111, v111
	v_add_f32_e32 v251, v251, v109
	v_mfma_f32_32x32x16_bf16 v[82:97], v[172:175], v[118:121], v[82:97]
	v_exp_f32_e32 v112, v112
	v_add_f32_e32 v251, v251, v110
	v_exp_f32_e32 v113, v113
	v_add_f32_e32 v251, v251, v111
	v_mfma_f32_32x32x16_bf16 v[82:97], v[176:179], v[114:117], v[82:97]
	v_cvt_pk_bf16_f32 v102, v106, v107
	v_add_f32_e32 v251, v251, v112
	v_cvt_pk_bf16_f32 v103, v108, v109
	v_cvt_pk_bf16_f32 v104, v110, v111
	v_cvt_pk_bf16_f32 v105, v112, v113
	v_add_f32_e32 v251, v251, v113
	v_add_f32_e32 v218, v218, v251
	s_add_i32 s94, s94, 1
	s_add_i32 s0, s94, 1
	s_lshr_b32 s57, s0, 1
	s_add_i32 s1, s93, 1
	s_cmp_le_u32 s57, s1
	s_cbranch_scc1 .Lq_w4
	s_waitcnt vmcnt(0)
	s_branch .Lq_wd

; __device__ __forceinline__ void diff_unit_lds(LAS unsigned char* lds, const bf16* Qd, const bf16* Kd, const bf16* VdT, bf16* MIX, const float* ghead, float lam, int head, int u, int wave, int lane) {
;     ...
;             for (int ds = 0; ds < 4; ++ds) S0 = MFMA32(*(const LAS bf16x8*)(st + koff + (((2 * ds + h) ^ kx) << 4)), qf[ds], S0);
;             if (!part) {
; #pragma unroll
;                 for (int ds = 0; ds < 4; ++ds) S1 = MFMA32(*(const LAS bf16x8*)(st + koff + 4096 + (((2 * ds + h) ^ kx) << 4)), qf[ds], S1);
;             }
;             float tmax = S0[0];
; #pragma unroll
;             for (int i = 1; i < 16; ++i) tmax = fmaxf(tmax, S0[i]);
;             if (masked) tmax = -1e30f;
;             if (!part) {
; #pragma unroll
;                 for (int i = 0; i < 16; ++i) tmax = fmaxf(tmax, S1[i]);
;             }
;             tmax = fmaxf(tmax, xhalf(tmax, h));
;             if (T == 0 || __any(tmax > 8.0f)) {
;                 const float delta = (T == 0) ? tmax : fmaxf(tmax, 0.f), alpha = (T == 0) ? 1.0f : __builtin_amdgcn_exp2f(-delta);
;                 l *= alpha;
; #pragma unroll
;                 for (int b = 0; b < 4; ++b)
; #pragma unroll
;                     for (int i = 0; i < 16; ++i) O[b][i] *= alpha;
;                 m_used += delta;
; #pragma unroll
;                 for (int i = 0; i < 16; ++i) { NEGM[i] = -m_used; S0[i] -= delta; S1[i] -= delta; }
;             }
;             {
;                 float p[16]; float ps = 0.f;
; #pragma unroll
;                 for (int i = 0; i < 16; ++i) { p[i] = __builtin_amdgcn_exp2f(S0[i]); ps += p[i]; }
;                 if (masked) {
; #pragma unroll
;                     for (int i = 0; i < 16; ++i) p[i] = 0.f;
;                     ps = 0.f;
;                 }
;                 l += ps;
;                 const bf16x8 pk0 = pack8(p[0], p[1], p[2], p[3], p[4], p[5], p[6], p[7]);
;                 const bf16x8 pk1 = pack8(p[8], p[9], p[10], p[11], p[12], p[13], p[14], p[15]);
; #pragma unroll
;                 for (int b = 0; b < 4; ++b) {
;                     const bf16x8 v0 = *(const LAS bf16x8*)(st + voff + b * 4096 + (((2 * h) ^ vx) << 4));
;                     const bf16x8 v1 = *(const LAS bf16x8*)(st + voff + b * 4096 + (((2 * h + 1) ^ vx) << 4));
;                     O[b] = MFMA32(v0, pk0, O[b]); O[b] = MFMA32(v1, pk1, O[b]);
;                 }
;             }
.Lq_rec_od:
	v_mfma_f32_32x32x16_bf16 v[2:17], v[234:237], v[98:101], v[2:17]
	ds_read_b128 v[234:237], v208 offset:28672
	s_add_i32 s0, s1, 0x6000
	s_mov_b32 m0, s0
	v_lshl_add_u64 v[186:187], v[162:163], 0, s[8:9]
	global_load_lds_dwordx4 v[186:187], off
	s_mov_b32 m0, s7
	v_exp_f32_e32 v82, v82
	v_exp_f32_e32 v83, v83
	v_exp_f32_e32 v84, v84
	v_mfma_f32_32x32x16_bf16 v[50:65], v[238:241], v[102:105], v[50:65]
	ds_read_b128 v[238:241], v213 offset:16384
	v_add_f32_e32 v251, v82, v83
	v_exp_f32_e32 v85, v85
	v_exp_f32_e32 v86, v86
	v_add_f32_e32 v251, v251, v84
	v_mfma_f32_32x32x16_bf16 v[34:49], v[242:245], v[102:105], v[34:49]
	ds_read_b128 v[242:245], v213 offset:20480
	v_exp_f32_e32 v87, v87
	v_add_f32_e32 v251, v251, v85
	v_exp_f32_e32 v88, v88
	v_add_f32_e32 v251, v251, v86
	v_mfma_f32_32x32x16_bf16 v[18:33], v[246:249], v[102:105], v[18:33]
	ds_read_b128 v[246:249], v213 offset:24576
	v_exp_f32_e32 v89, v89
	v_add_f32_e32 v251, v251, v87
	v_cvt_pk_bf16_f32 v82, v82, v83
	v_add_f32_e32 v251, v251, v88
	v_cvt_pk_bf16_f32 v83, v84, v85
	v_mfma_f32_32x32x16_bf16 v[2:17], v[252:255], v[102:105], v[2:17]
	ds_read_b128 v[252:255], v213 offset:28672
	v_cvt_pk_bf16_f32 v84, v86, v87
	v_cvt_pk_bf16_f32 v85, v88, v89
	v_add_f32_e32 v251, v251, v89
	v_exp_f32_e32 v90, v90
	v_exp_f32_e32 v91, v91
	s_cmp_lg_u32 s59, 0
	s_cbranch_scc1 .Lq_rl_od
.Lq_rlc_od:
	s_waitcnt lgkmcnt(8)
	v_mfma_f32_32x32x16_bf16 v[98:113], v[164:167], v[126:129], v[66:81]
	v_exp_f32_e32 v92, v92
	v_add_f32_e32 v251, v251, v90
	v_exp_f32_e32 v93, v93
	v_add_f32_e32 v251, v251, v91
	v_mfma_f32_32x32x16_bf16 v[98:113], v[168:171], v[122:125], v[98:113]
	v_exp_f32_e32 v94, v94
	v_add_f32_e32 v251, v251, v92
	v_exp_f32_e32 v95, v95
	v_add_f32_e32 v251, v251, v93
	v_mfma_f32_32x32x16_bf16 v[98:113], v[172:175], v[118:121], v[98:113]
	v_exp_f32_e32 v96, v96
	v_add_f32_e32 v251, v251, v94
	v_exp_f32_e32 v97, v97
	v_add_f32_e32 v251, v251, v95
	v_mfma_f32_32x32x16_bf16 v[98:113], v[176:179], v[114:117], v[98:113]
	v_cvt_pk_bf16_f32 v86, v90, v91
	v_add_f32_e32 v251, v251, v96
	v_cvt_pk_bf16_f32 v87, v92, v93
	v_cvt_pk_bf16_f32 v88, v94, v95
	v_cvt_pk_bf16_f32 v89, v96, v97
	v_add_f32_e32 v251, v251, v97
	v_add_f32_e32 v218, v218, v251
	s_branch .Lq_odd_join

; __device__ __forceinline__ void diff_unit_lds(LAS unsigned char* lds, const bf16* Qd, const bf16* Kd, const bf16* VdT, bf16* MIX, const float* ghead, float lam, int head, int u, int wave, int lane) {
;     ...
;             for (int ds = 0; ds < 4; ++ds) S0 = MFMA32(*(const LAS bf16x8*)(st + koff + (((2 * ds + h) ^ kx) << 4)), qf[ds], S0);
;             if (!part) {
; #pragma unroll
;                 for (int ds = 0; ds < 4; ++ds) S1 = MFMA32(*(const LAS bf16x8*)(st + koff + 4096 + (((2 * ds + h) ^ kx) << 4)), qf[ds], S1);
;             }
;             float tmax = S0[0];
; #pragma unroll
;             for (int i = 1; i < 16; ++i) tmax = fmaxf(tmax, S0[i]);
;             if (masked) tmax = -1e30f;
;             if (!part) {
; #pragma unroll
;                 for (int i = 0; i < 16; ++i) tmax = fmaxf(tmax, S1[i]);
;             }
;             tmax = fmaxf(tmax, xhalf(tmax, h));
;             if (T == 0 || __any(tmax > 8.0f)) {
;                 const float delta = (T == 0) ? tmax : fmaxf(tmax, 0.f), alpha = (T == 0) ? 1.0f : __builtin_amdgcn_exp2f(-delta);
;                 l *= alpha;
; #pragma unroll
;                 for (int b = 0; b < 4; ++b)
; #pragma unroll
;                     for (int i = 0; i < 16; ++i) O[b][i] *= alpha;
;                 m_used += delta;
; #pragma unroll
;                 for (int i = 0; i < 16; ++i) { NEGM[i] = -m_used; S0[i] -= delta; S1[i] -= delta; }
;             }
;             {
;                 float p[16]; float ps = 0.f;
; #pragma unroll
;                 for (int i = 0; i < 16; ++i) { p[i] = __builtin_amdgcn_exp2f(S0[i]); ps += p[i]; }
;                 if (masked) {
; #pragma unroll
;                     for (int i = 0; i < 16; ++i) p[i] = 0.f;
;                     ps = 0.f;
;                 }
;                 l += ps;
;                 const bf16x8 pk0 = pack8(p[0], p[1], p[2], p[3], p[4], p[5], p[6], p[7]);
;                 const bf16x8 pk1 = pack8(p[8], p[9], p[10], p[11], p[12], p[13], p[14], p[15]);
; #pragma unroll
;                 for (int b = 0; b < 4; ++b) {
;                     const bf16x8 v0 = *(const LAS bf16x8*)(st + voff + b * 4096 + (((2 * h) ^ vx) << 4));
;                     const bf16x8 v1 = *(const LAS bf16x8*)(st + voff + b * 4096 + (((2 * h + 1) ^ vx) << 4));
;                     O[b] = MFMA32(v0, pk0, O[b]); O[b] = MFMA32(v1, pk1, O[b]);
;                 }
;             }
.Lq_rec_on:
	v_mfma_f32_32x32x16_bf16 v[2:17], v[234:237], v[98:101], v[2:17]
	ds_read_b128 v[234:237], v208 offset:28672
	v_exp_f32_e32 v82, v82
	v_exp_f32_e32 v83, v83
	v_exp_f32_e32 v84, v84
	v_mfma_f32_32x32x16_bf16 v[50:65], v[238:241], v[102:105], v[50:65]
	ds_read_b128 v[238:241], v213 offset:16384
	v_add_f32_e32 v251, v82, v83
	v_exp_f32_e32 v85, v85
	v_exp_f32_e32 v86, v86
	v_add_f32_e32 v251, v251, v84
	v_mfma_f32_32x32x16_bf16 v[34:49], v[242:245], v[102:105], v[34:49]
	ds_read_b128 v[242:245], v213 offset:20480
	v_exp_f32_e32 v87, v87
	v_add_f32_e32 v251, v251, v85
	v_exp_f32_e32 v88, v88
	v_add_f32_e32 v251, v251, v86
	v_mfma_f32_32x32x16_bf16 v[18:33], v[246:249], v[102:105], v[18:33]
	ds_read_b128 v[246:249], v213 offset:24576
	v_exp_f32_e32 v89, v89
	v_add_f32_e32 v251, v251, v87
	v_cvt_pk_bf16_f32 v82, v82, v83
	v_add_f32_e32 v251, v251, v88
	v_cvt_pk_bf16_f32 v83, v84, v85
	v_mfma_f32_32x32x16_bf16 v[2:17], v[252:255], v[102:105], v[2:17]
	ds_read_b128 v[252:255], v213 offset:28672
	v_cvt_pk_bf16_f32 v84, v86, v87
	v_cvt_pk_bf16_f32 v85, v88, v89
	v_add_f32_e32 v251, v251, v89
	v_exp_f32_e32 v90, v90
	v_exp_f32_e32 v91, v91
	s_cmp_lg_u32 s59, 0
	s_cbranch_scc1 .Lq_rl_on
.Lq_rlc_on:
	s_waitcnt lgkmcnt(8)
	v_mfma_f32_32x32x16_bf16 v[98:113], v[164:167], v[126:129], v[66:81]
	v_exp_f32_e32 v92, v92
	v_add_f32_e32 v251, v251, v90
	v_exp_f32_e32 v93, v93
	v_add_f32_e32 v251, v251, v91
	v_mfma_f32_32x32x16_bf16 v[98:113], v[168:171], v[122:125], v[98:113]
	v_exp_f32_e32 v94, v94
	v_add_f32_e32 v251, v251, v92
	v_exp_f32_e32 v95, v95
	v_add_f32_e32 v251, v251, v93
	v_mfma_f32_32x32x16_bf16 v[98:113], v[172:175], v[118:121], v[98:113]
	v_exp_f32_e32 v96, v96
	v_add_f32_e32 v251, v251, v94
	v_exp_f32_e32 v97, v97
	v_add_f32_e32 v251, v251, v95
	v_mfma_f32_32x32x16_bf16 v[98:113], v[176:179], v[114:117], v[98:113]
	v_cvt_pk_bf16_f32 v86, v90, v91
	v_add_f32_e32 v251, v251, v96
	v_cvt_pk_bf16_f32 v87, v92, v93
	v_cvt_pk_bf16_f32 v88, v94, v95
	v_cvt_pk_bf16_f32 v89, v96, v97
	v_add_f32_e32 v251, v251, v97
	v_add_f32_e32 v218, v218, v251

; #define LAS __attribute__((address_space(3)))
; #define MFMA32(a, b, c) __builtin_amdgcn_mfma_f32_32x32x16_bf16((a), (b), (c), 0, 0, 0)
; __device__ __forceinline__ void diff_unit_lds(LAS unsigned char* lds, const bf16* Qd, const bf16* Kd, const bf16* VdT, bf16* MIX, const float* ghead, float lam, int head, int u, int wave, int lane) {
;     ...
;             {
;                 float p[16]; float ps = 0.f;
; #pragma unroll
;                 for (int i = 0; i < 16; ++i) { p[i] = __builtin_amdgcn_exp2f(S0[i]); ps += p[i]; }
;                 if (masked) {
; #pragma unroll
;                     for (int i = 0; i < 16; ++i) p[i] = 0.f;
;                     ps = 0.f;
;                 }
;                 l += ps;
;                 const bf16x8 pk0 = pack8(p[0], p[1], p[2], p[3], p[4], p[5], p[6], p[7]);
;                 const bf16x8 pk1 = pack8(p[8], p[9], p[10], p[11], p[12], p[13], p[14], p[15]);
; #pragma unroll
;                 for (int b = 0; b < 4; ++b) {
;                     const bf16x8 v0 = *(const LAS bf16x8*)(st + voff + b * 4096 + (((2 * h) ^ vx) << 4));
;                     const bf16x8 v1 = *(const LAS bf16x8*)(st + voff + b * 4096 + (((2 * h + 1) ^ vx) << 4));
;                     O[b] = MFMA32(v0, pk0, O[b]); O[b] = MFMA32(v1, pk1, O[b]);
;                 }
.Lq_rec_m:
	v_mfma_f32_32x32x16_bf16 v[2:17], v[234:237], v[82:85], v[2:17]
	ds_read_b128 v[234:237], v208 offset:28672
	v_exp_f32_e32 v98, v98
	v_exp_f32_e32 v99, v99
	v_exp_f32_e32 v100, v100
	v_add_f32_e32 v251, v98, v99
	v_exp_f32_e32 v101, v101
	v_exp_f32_e32 v102, v102
	v_add_f32_e32 v251, v251, v100
	v_mfma_f32_32x32x16_bf16 v[50:65], v[238:241], v[86:89], v[50:65]
	ds_read_b128 v[238:241], v213 offset:16384
	v_exp_f32_e32 v103, v103
	v_add_f32_e32 v251, v251, v101
	v_exp_f32_e32 v104, v104
	v_add_f32_e32 v251, v251, v102
	v_exp_f32_e32 v105, v105
	v_add_f32_e32 v251, v251, v103
	v_cvt_pk_bf16_f32 v98, v98, v99
	v_add_f32_e32 v251, v251, v104
	v_cvt_pk_bf16_f32 v99, v100, v101
	v_cvt_pk_bf16_f32 v100, v102, v103
	v_cvt_pk_bf16_f32 v101, v104, v105
	v_mfma_f32_32x32x16_bf16 v[34:49], v[242:245], v[86:89], v[34:49]
	ds_read_b128 v[242:245], v213 offset:20480
	v_add_f32_e32 v251, v251, v105
	v_exp_f32_e32 v106, v106
	v_exp_f32_e32 v107, v107
	v_exp_f32_e32 v108, v108
	v_add_f32_e32 v251, v251, v106
	v_exp_f32_e32 v109, v109
	v_add_f32_e32 v251, v251, v107
	v_exp_f32_e32 v110, v110
	v_mfma_f32_32x32x16_bf16 v[18:33], v[246:249], v[86:89], v[18:33]
	ds_read_b128 v[246:249], v213 offset:24576
	v_add_f32_e32 v251, v251, v108
	v_exp_f32_e32 v111, v111
	v_add_f32_e32 v251, v251, v109
	v_exp_f32_e32 v112, v112
	v_add_f32_e32 v251, v251, v110
	v_exp_f32_e32 v113, v113
	v_add_f32_e32 v251, v251, v111
	v_cvt_pk_bf16_f32 v102, v106, v107
	v_add_f32_e32 v251, v251, v112
	v_mfma_f32_32x32x16_bf16 v[2:17], v[252:255], v[86:89], v[2:17]
	ds_read_b128 v[252:255], v213 offset:28672
	v_cvt_pk_bf16_f32 v103, v108, v109
	v_cvt_pk_bf16_f32 v104, v110, v111
	v_cvt_pk_bf16_f32 v105, v112, v113
	v_add_f32_e32 v251, v251, v113
	v_cndmask_b32_e64 v98, v98, 0, s[2:3]
	v_cndmask_b32_e64 v99, v99, 0, s[2:3]
	v_cndmask_b32_e64 v100, v100, 0, s[2:3]
	v_cndmask_b32_e64 v101, v101, 0, s[2:3]
	v_cndmask_b32_e64 v102, v102, 0, s[2:3]
	v_cndmask_b32_e64 v103, v103, 0, s[2:3]
	v_cndmask_b32_e64 v104, v104, 0, s[2:3]
	v_cndmask_b32_e64 v105, v105, 0, s[2:3]
	v_cndmask_b32_e64 v251, v251, 0, s[2:3]
	s_cmp_lg_u32 s59, 0
	s_cbranch_scc1 .Lq_rl_m
